# per-half A/B of the static priority raise (asm guide 6.3): s_setprio 1 given to the older wave half (wr==0, waves 0-3) in all five K-loops instead of the younger half
# speedup vs baseline: 1.0016x; 1.0016x over previous
; template <class Epi, class Sched>
; __device__ __forceinline__ void gemm_phase(LAS unsigned char* lds, const Gemm g, const Sched& S, const Epi& E) {
;     ...
;         const bool has_next = S.next(ui + 1, nxt);
;         const char* nA = has_next ? (const char*)g.A + (size_t)nxt.pm * tstepA + (size_t)nxt.pn * apn : cA; const char* nB = has_next ? (const char*)g.Bt + (size_t)nxt.pn * tstepB : cB;
;         for (int t = 0; t < nt; t += 2) {
;             const bool last = (t == nt - 2);
;             const char* a1 = cA + (size_t)(t + 1) * kstep;
;             const char* a2 = last ? nA : cA + (size_t)(t + 2) * kstep; const char* b2 = last ? nB : cB + (size_t)(t + 2) * kstep;
;             const char* a3 = a2 + kstep; const char* b3 = b2 + kstep;
.LBB0_95:
	s_ashr_i32 s13, s12, 31
	s_lshl_b64 s[6:7], s[12:13], 19
	s_add_u32 s46, s84, s6
	s_addc_u32 s47, s85, s7
	s_and_b64 s[6:7], s[50:51], exec
	s_cselect_b32 s13, s47, s43
	s_cselect_b32 s57, s46, s42
	s_ashr_i32 s45, s44, 31
	s_lshl_b64 s[6:7], s[44:45], 19
	s_add_u32 s48, s8, s6
	s_addc_u32 s49, s9, s7
	s_and_b64 s[6:7], s[50:51], exec
	s_cselect_b32 s45, s49, s53
	s_cselect_b32 s68, s48, s52
	s_add_u32 s42, s42, 0x40080
	s_addc_u32 s43, s43, 0
	s_add_u32 s52, s52, 0x100
	s_addc_u32 s53, s53, 0
	s_mov_b32 s69, -2
	s_cmp_eq_u64 s[18:19], 0
	s_cbranch_scc1 .Lprio_96
	s_setprio 1

; template <class Epi, class Sched>
; __device__ __forceinline__ void gemm_phase(LAS unsigned char* lds, const Gemm g, const Sched& S, const Epi& E) {
;     ...
;         const bool has_next = S.next(ui + 1, nxt);
;         const char* nA = has_next ? (const char*)g.A + (size_t)nxt.pm * tstepA + (size_t)nxt.pn * apn : cA; const char* nB = has_next ? (const char*)g.Bt + (size_t)nxt.pn * tstepB : cB;
;         for (int t = 0; t < nt; t += 2) {
;             const bool last = (t == nt - 2);
;             const char* a1 = cA + (size_t)(t + 1) * kstep;
;             const char* a2 = last ? nA : cA + (size_t)(t + 2) * kstep; const char* b2 = last ? nB : cB + (size_t)(t + 2) * kstep;
;             const char* a3 = a2 + kstep; const char* b3 = b2 + kstep;
.LBB0_357:
	s_ashr_i32 s43, s42, 31
	s_lshl_b64 s[6:7], s[42:43], 19
	v_readlane_b32 s14, v253, 21
	v_readlane_b32 s15, v253, 22
	s_add_u32 s46, s14, s6
	s_addc_u32 s47, s15, s7
	s_and_b64 s[6:7], s[44:45], exec
	s_cselect_b32 s9, s47, s53
	s_cselect_b32 s13, s46, s52
	s_ashr_i32 s23, s22, 31
	s_lshl_b64 s[6:7], s[22:23], 19
	s_add_u32 s48, s28, s6
	s_addc_u32 s49, s35, s7
	s_and_b64 s[6:7], s[44:45], exec
	s_cselect_b32 s21, s49, s55
	s_cselect_b32 s23, s48, s54
	s_add_u32 s52, s52, 0x40080
	s_addc_u32 s53, s53, 0
	s_add_u32 s33, s54, 0x100
	s_addc_u32 s43, s55, 0
	s_mov_b32 s54, -2
	s_waitcnt lgkmcnt(0)
	s_cmp_eq_u64 s[18:19], 0
	s_cbranch_scc1 .Lprio_358
	s_setprio 1

; template <class Epi, class Sched>
; __device__ __forceinline__ void gemm_phase(LAS unsigned char* lds, const Gemm g, const Sched& S, const Epi& E) {
;     ...
;         const bool has_next = S.next(ui + 1, nxt);
;         const char* nA = has_next ? (const char*)g.A + (size_t)nxt.pm * tstepA + (size_t)nxt.pn * apn : cA; const char* nB = has_next ? (const char*)g.Bt + (size_t)nxt.pn * tstepB : cB;
;         for (int t = 0; t < nt; t += 2) {
;             const bool last = (t == nt - 2);
;             const char* a1 = cA + (size_t)(t + 1) * kstep;
;             const char* a2 = last ? nA : cA + (size_t)(t + 2) * kstep; const char* b2 = last ? nB : cB + (size_t)(t + 2) * kstep;
;             const char* a3 = a2 + kstep; const char* b3 = b2 + kstep;
.LBB0_627:
	s_lshl_b64 s[6:7], s[22:23], 17
	s_add_u32 s46, s28, s6
	s_addc_u32 s47, s20, s7
	s_and_b64 s[6:7], exec, s[42:43]
	s_cselect_b32 s9, s47, s51
	s_cselect_b32 s13, s46, s50
	s_mov_b32 s6, 0
	s_mov_b64 s[54:55], -1
	s_mov_b64 s[56:57], 0
	s_waitcnt lgkmcnt(0)
	s_cmp_eq_u64 s[18:19], 0
	s_cbranch_scc1 .Lprio_628
	s_setprio 1

; template <class Epi, class Sched>
; __device__ __forceinline__ void gemm_phase(LAS unsigned char* lds, const Gemm g, const Sched& S, const Epi& E) {
;     ...
;         const bool has_next = S.next(ui + 1, nxt);
;         const char* nA = has_next ? (const char*)g.A + (size_t)nxt.pm * tstepA + (size_t)nxt.pn * apn : cA; const char* nB = has_next ? (const char*)g.Bt + (size_t)nxt.pn * tstepB : cB;
;         for (int t = 0; t < nt; t += 2) {
;             const bool last = (t == nt - 2);
;             const char* a1 = cA + (size_t)(t + 1) * kstep;
;             const char* a2 = last ? nA : cA + (size_t)(t + 2) * kstep; const char* b2 = last ? nB : cB + (size_t)(t + 2) * kstep;
;             const char* a3 = a2 + kstep; const char* b3 = b2 + kstep;
.LBB0_717:
	s_ashr_i32 s23, s22, 31
	s_lshl_b64 s[14:15], s[22:23], 19
	s_add_u32 s34, s84, s14
	s_addc_u32 s35, s85, s15
	s_and_b64 s[14:15], s[42:43], exec
	s_cselect_b32 s23, s35, s7
	s_cselect_b32 s53, s34, s6
	s_ashr_i32 s19, s18, 31
	s_lshl_b64 s[14:15], s[18:19], 19
	s_add_u32 s40, s28, s14
	s_addc_u32 s41, s48, s15
	s_and_b64 s[14:15], s[42:43], exec
	s_cselect_b32 s19, s41, s47
	s_cselect_b32 s54, s40, s46
	s_add_u32 s44, s6, 0x40080
	s_addc_u32 s45, s7, 0
	s_add_u32 s46, s46, 0x100
	s_addc_u32 s47, s47, 0
	s_mov_b32 s55, -2
	s_cmp_eq_u64 s[16:17], 0
	s_cbranch_scc1 .Lprio_gu
	s_setprio 1

; template <class Epi, class Sched>
; __device__ __forceinline__ void gemm_phase(LAS unsigned char* lds, const Gemm g, const Sched& S, const Epi& E) {
;     ...
;         const bool has_next = S.next(ui + 1, nxt);
;         const char* nA = has_next ? (const char*)g.A + (size_t)nxt.pm * tstepA + (size_t)nxt.pn * apn : cA; const char* nB = has_next ? (const char*)g.Bt + (size_t)nxt.pn * tstepB : cB;
;         for (int t = 0; t < nt; t += 2) {
;             const bool last = (t == nt - 2);
;             const char* a1 = cA + (size_t)(t + 1) * kstep;
;             const char* a2 = last ? nA : cA + (size_t)(t + 2) * kstep; const char* b2 = last ? nB : cB + (size_t)(t + 2) * kstep;
;             const char* a3 = a2 + kstep; const char* b3 = b2 + kstep;
.LBB0_806:
	s_add_u32 s33, s46, 0x100
	s_addc_u32 s53, s47, 0
	s_mov_b32 s54, -2
	s_waitcnt lgkmcnt(0)
	s_cmp_eq_u64 s[18:19], 0
	s_cbranch_scc1 .Lprio_807
	s_setprio 1
